# dil second-round rebalance + sentinel loads in in-proj RoPE epilogue
# speedup vs baseline: 1.0048x; 1.0023x over previous
; __device__ __forceinline__ u32x4 pack8(const f32x4& a, const f32x4& b) { u32x4 w; w.x = cvt_pk_bf16(a[0], a[1]); w.y = cvt_pk_bf16(a[2], a[3]); w.z = cvt_pk_bf16(b[0], b[1]); w.w = cvt_pk_bf16(b[2], b[3]); return w; }
;     __device__ __forceinline__ void operator()(const f32x4 (&acc)[2][2][4][2], const Unit& u, int wr, int wc, int fr, int fq) const {
;     ...
;             float sc; int i0, d1, dd, tp; const float *ct, *st;
;             if (type == 1) { sc = pn < 4 ? SC_A : 1.f; i0 = 8 * fq; d1 = pn * BM + 64 * wc + i0; dd = 32; tp = 32; ct = cosA; st = sinA; }
;             else { const bool isq = (pn < 16) || (pn == 16 && wc < 2); sc = isq ? SC_B : 1.f; i0 = 32 * (wc & 1) + 8 * fq; d1 = pn * BM + 128 * (wc >> 1) + i0; dd = 64; tp = 64; ct = cosB; st = sinB; }
; #pragma unroll
;             for (int ai = 0; ai < 2; ++ai)
; #pragma unroll
;                 for (int m = 0; m < 4; ++m) { const int row = row0 + ai * HALF + m * 16, pos = row & (SEQ - 1); const float scr = sc * rs[ai][m];
;                     const f32x4 c0 = *(const f32x4*)(ct + pos * tp + i0), c1 = *(const f32x4*)(ct + pos * tp + i0 + 4), s0 = *(const f32x4*)(st + pos * tp + i0), s1 = *(const f32x4*)(st + pos * tp + i0 + 4);
;                     const f32x4 x10 = acc[ai][0][m][0], x11 = acc[ai][0][m][1], x20 = acc[ai][1][m][0], x21 = acc[ai][1][m][1];
;                     const f32x4 a0 = (x10 * c0 - x20 * s0) * scr, a1 = (x11 * c1 - x21 * s1) * scr, b0 = (x10 * s0 + x20 * c0) * scr, b1 = (x11 * s1 + x21 * c1) * scr;
;                     bf16_t* rowp = O + (size_t)row * LDP + d1;
;                     *(u32x4*)(rowp) = pack8(a0, a1); *(u32x4*)(rowp + dd) = pack8(b0, b1); }
.LBB0_295:
	s_add_u32 s8, s14, s8
	s_addc_u32 s9, s15, s9
	s_add_u32 s6, s14, s6
	v_lshlrev_b32_e32 v178, 2, v130
	v_and_b32_e32 v130, 0xfcf, v154
	s_addc_u32 s7, s15, s7
	v_mul_u32_u24_e32 v130, s0, v130
	v_lshl_add_u64 v[172:173], s[6:7], 0, v[178:179]
	v_lshl_add_u64 v[188:189], s[8:9], 0, v[178:179]
	v_lshlrev_b32_e32 v178, 2, v130
	v_lshl_add_u64 v[130:131], v[188:189], 0, v[178:179]
	global_load_dwordx4 v[142:145], v[130:131], off
	global_load_dwordx4 v[138:141], v[130:131], off offset:16
	v_lshl_add_u64 v[130:131], v[172:173], 0, v[178:179]
	global_load_dwordx4 v[134:137], v[130:131], off
	s_nop 0
	global_load_dwordx4 v[130:133], v[130:131], off offset:16
	global_load_dword v223, v[188:189], off
	global_load_dword v223, v[188:189], off
	v_lshl_or_b32 v176, s53, 8, v174
	v_mul_f32_e32 v190, v158, v222
	v_mov_b64_e32 v[174:175], s[18:19]
	v_and_b32_e32 v178, 0xfdf, v191
	v_ashrrev_i32_e32 v177, 31, v176
	v_mad_i64_i32 v[194:195], s[6:7], v154, s33, v[174:175]
	v_mul_u32_u24_e32 v178, s0, v178
	v_lshlrev_b64 v[176:177], 1, v[176:177]
	v_lshl_add_u64 v[194:195], v[194:195], 0, v[176:177]
	s_lshl_b32 s58, s0, 1
	v_lshlrev_b32_e32 v178, 2, v178
	v_lshl_add_u64 v[206:207], v[194:195], 0, s[58:59]
	v_lshl_add_u64 v[208:209], v[188:189], 0, v[178:179]
	s_waitcnt vmcnt(5)
	v_pk_mul_f32 v[210:211], v[116:117], v[144:145]
	v_pk_mul_f32 v[212:213], v[114:115], v[142:143]
	s_waitcnt vmcnt(4)
	v_pk_mul_f32 v[224:225], v[108:109], v[140:141]
	v_pk_mul_f32 v[226:227], v[106:107], v[138:139]
	v_pk_mul_f32 v[144:145], v[128:129], v[144:145]
	v_pk_mul_f32 v[142:143], v[126:127], v[142:143]
	v_pk_mul_f32 v[140:141], v[124:125], v[140:141]
	v_pk_mul_f32 v[138:139], v[122:123], v[138:139]
	s_waitcnt vmcnt(3)
	v_pk_fma_f32 v[210:211], v[128:129], v[136:137], v[210:211] neg_lo:[0,0,1] neg_hi:[0,0,1]
	v_pk_fma_f32 v[212:213], v[126:127], v[134:135], v[212:213] neg_lo:[0,0,1] neg_hi:[0,0,1]
	s_waitcnt vmcnt(2)
	v_pk_fma_f32 v[224:225], v[124:125], v[132:133], v[224:225] neg_lo:[0,0,1] neg_hi:[0,0,1]
	v_pk_fma_f32 v[226:227], v[122:123], v[130:131], v[226:227] neg_lo:[0,0,1] neg_hi:[0,0,1]
	v_pk_fma_f32 v[136:137], v[116:117], v[136:137], v[144:145]
	v_pk_fma_f32 v[134:135], v[114:115], v[134:135], v[142:143]
	v_pk_fma_f32 v[132:133], v[108:109], v[132:133], v[140:141]
	v_pk_fma_f32 v[130:131], v[106:107], v[130:131], v[138:139]
	v_pk_mul_f32 v[138:139], v[190:191], v[210:211] op_sel_hi:[0,1]
	v_pk_mul_f32 v[140:141], v[190:191], v[212:213] op_sel_hi:[0,1]
	v_pk_mul_f32 v[142:143], v[190:191], v[224:225] op_sel_hi:[0,1]
	v_pk_mul_f32 v[144:145], v[190:191], v[226:227] op_sel_hi:[0,1]
	v_pk_mul_f32 v[136:137], v[190:191], v[136:137] op_sel_hi:[0,1]
	v_pk_mul_f32 v[134:135], v[190:191], v[134:135] op_sel_hi:[0,1]
	v_pk_mul_f32 v[210:211], v[190:191], v[132:133] op_sel_hi:[0,1]
	v_pk_mul_f32 v[212:213], v[190:191], v[130:131] op_sel_hi:[0,1]
	v_cvt_pk_bf16_f32 v130, v140, v141
	v_cvt_pk_bf16_f32 v131, v138, v139
	v_cvt_pk_bf16_f32 v132, v144, v145
	v_cvt_pk_bf16_f32 v133, v142, v143
	v_cvt_pk_bf16_f32 v134, v134, v135
	v_cvt_pk_bf16_f32 v135, v136, v137
	v_cvt_pk_bf16_f32 v136, v212, v213
	v_cvt_pk_bf16_f32 v137, v210, v211
	global_store_dwordx4 v[194:195], v[130:133], off
	global_store_dwordx4 v[206:207], v[134:137], off
	global_load_dwordx4 v[130:133], v[208:209], off
	s_nop 0
	global_load_dwordx4 v[134:137], v[208:209], off offset:16
	v_lshl_add_u64 v[142:143], v[172:173], 0, v[178:179]
	global_load_dwordx4 v[138:141], v[142:143], off
	s_nop 0
	global_load_dwordx4 v[142:145], v[142:143], off offset:16
	global_load_dword v223, v[188:189], off
	global_load_dword v223, v[188:189], off
	v_mul_f32_e32 v190, v156, v222
	v_and_b32_e32 v178, 0xfef, v155
	v_mad_i64_i32 v[194:195], s[6:7], v191, s33, v[174:175]
	v_mul_u32_u24_e32 v178, s0, v178
	v_lshl_add_u64 v[194:195], v[194:195], 0, v[176:177]
	v_lshlrev_b32_e32 v178, 2, v178
	v_lshl_add_u64 v[206:207], v[194:195], 0, s[58:59]
	v_lshl_add_u64 v[208:209], v[188:189], 0, v[178:179]
	s_waitcnt vmcnt(5)
	v_pk_mul_f32 v[210:211], v[100:101], v[132:133]
	v_pk_mul_f32 v[212:213], v[98:99], v[130:131]
	s_waitcnt vmcnt(4)
	v_pk_mul_f32 v[224:225], v[92:93], v[136:137]
	v_pk_mul_f32 v[226:227], v[90:91], v[134:135]
	v_pk_mul_f32 v[132:133], v[120:121], v[132:133]
	v_pk_mul_f32 v[130:131], v[118:119], v[130:131]
	v_pk_mul_f32 v[136:137], v[112:113], v[136:137]
	v_pk_mul_f32 v[134:135], v[110:111], v[134:135]
	s_waitcnt vmcnt(3)
	v_pk_fma_f32 v[210:211], v[120:121], v[140:141], v[210:211] neg_lo:[0,0,1] neg_hi:[0,0,1]
	v_pk_fma_f32 v[212:213], v[118:119], v[138:139], v[212:213] neg_lo:[0,0,1] neg_hi:[0,0,1]
	s_waitcnt vmcnt(2)
; __device__ __forceinline__ u32x4 pack8(const f32x4& a, const f32x4& b) { u32x4 w; w.x = cvt_pk_bf16(a[0], a[1]); w.y = cvt_pk_bf16(a[2], a[3]); w.z = cvt_pk_bf16(b[0], b[1]); w.w = cvt_pk_bf16(b[2], b[3]); return w; }
;     __device__ __forceinline__ void operator()(const f32x4 (&acc)[2][2][4][2], const Unit& u, int wr, int wc, int fr, int fq) const {
;     ...
;                 for (int m = 0; m < 4; ++m) { const int row = row0 + ai * HALF + m * 16, pos = row & (SEQ - 1); const float scr = sc * rs[ai][m];
;                     const f32x4 c0 = *(const f32x4*)(ct + pos * tp + i0), c1 = *(const f32x4*)(ct + pos * tp + i0 + 4), s0 = *(const f32x4*)(st + pos * tp + i0), s1 = *(const f32x4*)(st + pos * tp + i0 + 4);
;                     const f32x4 x10 = acc[ai][0][m][0], x11 = acc[ai][0][m][1], x20 = acc[ai][1][m][0], x21 = acc[ai][1][m][1];
;                     const f32x4 a0 = (x10 * c0 - x20 * s0) * scr, a1 = (x11 * c1 - x21 * s1) * scr, b0 = (x10 * s0 + x20 * c0) * scr, b1 = (x11 * s1 + x21 * c1) * scr;
;                     bf16_t* rowp = O + (size_t)row * LDP + d1;
;                     *(u32x4*)(rowp) = pack8(a0, a1); *(u32x4*)(rowp + dd) = pack8(b0, b1); }
	v_pk_fma_f32 v[224:225], v[112:113], v[144:145], v[224:225] neg_lo:[0,0,1] neg_hi:[0,0,1]
	v_pk_fma_f32 v[226:227], v[110:111], v[142:143], v[226:227] neg_lo:[0,0,1] neg_hi:[0,0,1]
	v_pk_fma_f32 v[132:133], v[100:101], v[140:141], v[132:133]
	v_pk_fma_f32 v[130:131], v[98:99], v[138:139], v[130:131]
	v_pk_fma_f32 v[136:137], v[92:93], v[144:145], v[136:137]
	v_pk_fma_f32 v[134:135], v[90:91], v[142:143], v[134:135]
	v_pk_mul_f32 v[138:139], v[190:191], v[210:211] op_sel_hi:[0,1]
	v_pk_mul_f32 v[140:141], v[190:191], v[212:213] op_sel_hi:[0,1]
	v_pk_mul_f32 v[142:143], v[190:191], v[224:225] op_sel_hi:[0,1]
	v_pk_mul_f32 v[144:145], v[190:191], v[226:227] op_sel_hi:[0,1]
	v_pk_mul_f32 v[210:211], v[190:191], v[132:133] op_sel_hi:[0,1]
	v_pk_mul_f32 v[212:213], v[190:191], v[130:131] op_sel_hi:[0,1]
	v_pk_mul_f32 v[224:225], v[190:191], v[136:137] op_sel_hi:[0,1]
	v_pk_mul_f32 v[136:137], v[190:191], v[134:135] op_sel_hi:[0,1]
	v_cvt_pk_bf16_f32 v130, v140, v141
	v_cvt_pk_bf16_f32 v131, v138, v139
	v_cvt_pk_bf16_f32 v132, v144, v145
	v_cvt_pk_bf16_f32 v133, v142, v143
	v_cvt_pk_bf16_f32 v134, v212, v213
	v_cvt_pk_bf16_f32 v135, v210, v211
	v_cvt_pk_bf16_f32 v136, v136, v137
	v_cvt_pk_bf16_f32 v137, v224, v225
	global_store_dwordx4 v[194:195], v[130:133], off
	global_store_dwordx4 v[206:207], v[134:137], off
	global_load_dwordx4 v[130:133], v[208:209], off
	s_nop 0
	global_load_dwordx4 v[134:137], v[208:209], off offset:16
	v_lshl_add_u64 v[142:143], v[172:173], 0, v[178:179]
	global_load_dwordx4 v[138:141], v[142:143], off
	s_nop 0
	global_load_dwordx4 v[142:145], v[142:143], off offset:16
	global_load_dword v223, v[188:189], off
	global_load_dword v223, v[188:189], off
	v_mul_f32_e32 v190, v160, v222
	v_and_b32_e32 v178, 0xfff, v217
	v_mad_i64_i32 v[194:195], s[6:7], v155, s33, v[174:175]
	v_mul_u32_u24_e32 v178, s0, v178
	v_lshl_add_u64 v[194:195], v[194:195], 0, v[176:177]
	v_lshlrev_b32_e32 v178, 2, v178
	v_lshl_add_u64 v[206:207], v[194:195], 0, s[58:59]
	v_lshl_add_u64 v[208:209], v[188:189], 0, v[178:179]
	s_waitcnt vmcnt(5)
	v_pk_mul_f32 v[210:211], v[84:85], v[132:133]
	v_pk_mul_f32 v[212:213], v[82:83], v[130:131]
	s_waitcnt vmcnt(4)
	v_pk_mul_f32 v[224:225], v[76:77], v[136:137]
	v_pk_mul_f32 v[226:227], v[74:75], v[134:135]
	v_pk_mul_f32 v[132:133], v[104:105], v[132:133]
	v_pk_mul_f32 v[130:131], v[102:103], v[130:131]
	v_pk_mul_f32 v[136:137], v[96:97], v[136:137]
	v_pk_mul_f32 v[134:135], v[94:95], v[134:135]
	s_waitcnt vmcnt(3)
	v_pk_fma_f32 v[210:211], v[104:105], v[140:141], v[210:211] neg_lo:[0,0,1] neg_hi:[0,0,1]
	v_pk_fma_f32 v[212:213], v[102:103], v[138:139], v[212:213] neg_lo:[0,0,1] neg_hi:[0,0,1]
	s_waitcnt vmcnt(2)
	v_pk_fma_f32 v[224:225], v[96:97], v[144:145], v[224:225] neg_lo:[0,0,1] neg_hi:[0,0,1]
	v_pk_fma_f32 v[226:227], v[94:95], v[142:143], v[226:227] neg_lo:[0,0,1] neg_hi:[0,0,1]
	v_pk_fma_f32 v[132:133], v[84:85], v[140:141], v[132:133]
	v_pk_fma_f32 v[130:131], v[82:83], v[138:139], v[130:131]
	v_pk_fma_f32 v[136:137], v[76:77], v[144:145], v[136:137]
	v_pk_fma_f32 v[134:135], v[74:75], v[142:143], v[134:135]
	v_pk_mul_f32 v[138:139], v[190:191], v[210:211] op_sel_hi:[0,1]
	v_pk_mul_f32 v[140:141], v[190:191], v[212:213] op_sel_hi:[0,1]
	v_pk_mul_f32 v[142:143], v[190:191], v[224:225] op_sel_hi:[0,1]
	v_pk_mul_f32 v[144:145], v[190:191], v[226:227] op_sel_hi:[0,1]
	v_pk_mul_f32 v[210:211], v[190:191], v[132:133] op_sel_hi:[0,1]
	v_pk_mul_f32 v[212:213], v[190:191], v[130:131] op_sel_hi:[0,1]
	v_pk_mul_f32 v[224:225], v[190:191], v[136:137] op_sel_hi:[0,1]
	v_pk_mul_f32 v[136:137], v[190:191], v[134:135] op_sel_hi:[0,1]
	v_cvt_pk_bf16_f32 v130, v140, v141
	v_cvt_pk_bf16_f32 v131, v138, v139
	v_cvt_pk_bf16_f32 v132, v144, v145
	v_cvt_pk_bf16_f32 v133, v142, v143
	v_cvt_pk_bf16_f32 v134, v212, v213
	v_cvt_pk_bf16_f32 v135, v210, v211
	v_cvt_pk_bf16_f32 v136, v136, v137
	v_cvt_pk_bf16_f32 v137, v224, v225
	global_store_dwordx4 v[194:195], v[130:133], off
	global_store_dwordx4 v[206:207], v[134:137], off
	global_load_dwordx4 v[130:133], v[208:209], off
	s_nop 0
	global_load_dwordx4 v[134:137], v[208:209], off offset:16
	v_lshl_add_u64 v[142:143], v[172:173], 0, v[178:179]
	global_load_dwordx4 v[138:141], v[142:143], off
	s_nop 0
	global_load_dwordx4 v[142:145], v[142:143], off offset:16
	global_load_dword v223, v[188:189], off
	global_load_dword v223, v[188:189], off
	v_mul_f32_e32 v190, v162, v222
	v_and_b32_e32 v178, 0xfcf, v218
	v_mad_i64_i32 v[194:195], s[6:7], v217, s33, v[174:175]
	v_mul_u32_u24_e32 v178, s0, v178
	v_lshl_add_u64 v[194:195], v[194:195], 0, v[176:177]
	v_lshlrev_b32_e32 v178, 2, v178
	v_lshl_add_u64 v[206:207], v[194:195], 0, s[58:59]
	v_lshl_add_u64 v[208:209], v[188:189], 0, v[178:179]
	s_waitcnt vmcnt(5)
	v_pk_mul_f32 v[210:211], v[72:73], v[132:133]
	v_pk_mul_f32 v[212:213], v[70:71], v[130:131]
	s_waitcnt vmcnt(4)
	v_pk_mul_f32 v[224:225], v[68:69], v[136:137]
	v_pk_mul_f32 v[226:227], v[66:67], v[134:135]
	v_pk_mul_f32 v[132:133], v[88:89], v[132:133]
	v_pk_mul_f32 v[130:131], v[86:87], v[130:131]
	v_pk_mul_f32 v[136:137], v[80:81], v[136:137]
	v_pk_mul_f32 v[134:135], v[78:79], v[134:135]
	s_waitcnt vmcnt(3)
	v_pk_fma_f32 v[210:211], v[88:89], v[140:141], v[210:211] neg_lo:[0,0,1] neg_hi:[0,0,1]
	v_pk_fma_f32 v[212:213], v[86:87], v[138:139], v[212:213] neg_lo:[0,0,1] neg_hi:[0,0,1]
	s_waitcnt vmcnt(2)
; __device__ __forceinline__ u32x4 pack8(const f32x4& a, const f32x4& b) { u32x4 w; w.x = cvt_pk_bf16(a[0], a[1]); w.y = cvt_pk_bf16(a[2], a[3]); w.z = cvt_pk_bf16(b[0], b[1]); w.w = cvt_pk_bf16(b[2], b[3]); return w; }
;     __device__ __forceinline__ void operator()(const f32x4 (&acc)[2][2][4][2], const Unit& u, int wr, int wc, int fr, int fq) const {
;     ...
;                 for (int m = 0; m < 4; ++m) { const int row = row0 + ai * HALF + m * 16, pos = row & (SEQ - 1); const float scr = sc * rs[ai][m];
;                     const f32x4 c0 = *(const f32x4*)(ct + pos * tp + i0), c1 = *(const f32x4*)(ct + pos * tp + i0 + 4), s0 = *(const f32x4*)(st + pos * tp + i0), s1 = *(const f32x4*)(st + pos * tp + i0 + 4);
;                     const f32x4 x10 = acc[ai][0][m][0], x11 = acc[ai][0][m][1], x20 = acc[ai][1][m][0], x21 = acc[ai][1][m][1];
;                     const f32x4 a0 = (x10 * c0 - x20 * s0) * scr, a1 = (x11 * c1 - x21 * s1) * scr, b0 = (x10 * s0 + x20 * c0) * scr, b1 = (x11 * s1 + x21 * c1) * scr;
;                     bf16_t* rowp = O + (size_t)row * LDP + d1;
;                     *(u32x4*)(rowp) = pack8(a0, a1); *(u32x4*)(rowp + dd) = pack8(b0, b1); }
	v_pk_fma_f32 v[224:225], v[80:81], v[144:145], v[224:225] neg_lo:[0,0,1] neg_hi:[0,0,1]
	v_pk_fma_f32 v[226:227], v[78:79], v[142:143], v[226:227] neg_lo:[0,0,1] neg_hi:[0,0,1]
	v_pk_fma_f32 v[132:133], v[72:73], v[140:141], v[132:133]
	v_pk_fma_f32 v[130:131], v[70:71], v[138:139], v[130:131]
	v_pk_fma_f32 v[136:137], v[68:69], v[144:145], v[136:137]
	v_pk_fma_f32 v[134:135], v[66:67], v[142:143], v[134:135]
	v_pk_mul_f32 v[138:139], v[190:191], v[210:211] op_sel_hi:[0,1]
	v_pk_mul_f32 v[140:141], v[190:191], v[212:213] op_sel_hi:[0,1]
	v_pk_mul_f32 v[142:143], v[190:191], v[224:225] op_sel_hi:[0,1]
	v_pk_mul_f32 v[144:145], v[190:191], v[226:227] op_sel_hi:[0,1]
	v_pk_mul_f32 v[210:211], v[190:191], v[132:133] op_sel_hi:[0,1]
	v_pk_mul_f32 v[212:213], v[190:191], v[130:131] op_sel_hi:[0,1]
	v_pk_mul_f32 v[224:225], v[190:191], v[136:137] op_sel_hi:[0,1]
	v_pk_mul_f32 v[136:137], v[190:191], v[134:135] op_sel_hi:[0,1]
	v_cvt_pk_bf16_f32 v130, v140, v141
	v_cvt_pk_bf16_f32 v131, v138, v139
	v_cvt_pk_bf16_f32 v132, v144, v145
	v_cvt_pk_bf16_f32 v133, v142, v143
	v_cvt_pk_bf16_f32 v134, v212, v213
	v_cvt_pk_bf16_f32 v135, v210, v211
	v_cvt_pk_bf16_f32 v136, v136, v137
	v_cvt_pk_bf16_f32 v137, v224, v225
	global_store_dwordx4 v[194:195], v[130:133], off
	global_store_dwordx4 v[206:207], v[134:137], off
	global_load_dwordx4 v[130:133], v[208:209], off
	s_nop 0
	global_load_dwordx4 v[134:137], v[208:209], off offset:16
	v_lshl_add_u64 v[142:143], v[172:173], 0, v[178:179]
	global_load_dwordx4 v[138:141], v[142:143], off
	s_nop 0
	global_load_dwordx4 v[142:145], v[142:143], off offset:16
	global_load_dword v223, v[188:189], off
	global_load_dword v223, v[188:189], off
	v_mul_f32_e32 v190, v164, v222
	v_and_b32_e32 v178, 0xfdf, v219
	v_mad_i64_i32 v[194:195], s[6:7], v218, s33, v[174:175]
	v_mul_u32_u24_e32 v178, s0, v178
	v_lshl_add_u64 v[194:195], v[194:195], 0, v[176:177]
	v_lshlrev_b32_e32 v178, 2, v178
	v_lshl_add_u64 v[206:207], v[194:195], 0, s[58:59]
	v_lshl_add_u64 v[208:209], v[188:189], 0, v[178:179]
	s_waitcnt vmcnt(5)
	v_pk_mul_f32 v[210:211], v[52:53], v[132:133]
	v_pk_mul_f32 v[212:213], v[50:51], v[130:131]
	s_waitcnt vmcnt(4)
	v_pk_mul_f32 v[224:225], v[44:45], v[136:137]
	v_pk_mul_f32 v[226:227], v[42:43], v[134:135]
	v_pk_mul_f32 v[132:133], v[64:65], v[132:133]
	v_pk_mul_f32 v[130:131], v[62:63], v[130:131]
	v_pk_mul_f32 v[136:137], v[60:61], v[136:137]
	v_pk_mul_f32 v[134:135], v[58:59], v[134:135]
	s_waitcnt vmcnt(3)
	v_pk_fma_f32 v[210:211], v[64:65], v[140:141], v[210:211] neg_lo:[0,0,1] neg_hi:[0,0,1]
	v_pk_fma_f32 v[212:213], v[62:63], v[138:139], v[212:213] neg_lo:[0,0,1] neg_hi:[0,0,1]
	s_waitcnt vmcnt(2)
	v_pk_fma_f32 v[224:225], v[60:61], v[144:145], v[224:225] neg_lo:[0,0,1] neg_hi:[0,0,1]
	v_pk_fma_f32 v[226:227], v[58:59], v[142:143], v[226:227] neg_lo:[0,0,1] neg_hi:[0,0,1]
	v_pk_fma_f32 v[132:133], v[52:53], v[140:141], v[132:133]
	v_pk_fma_f32 v[130:131], v[50:51], v[138:139], v[130:131]
	v_pk_fma_f32 v[136:137], v[44:45], v[144:145], v[136:137]
	v_pk_fma_f32 v[134:135], v[42:43], v[142:143], v[134:135]
	v_pk_mul_f32 v[138:139], v[190:191], v[210:211] op_sel_hi:[0,1]
	v_pk_mul_f32 v[140:141], v[190:191], v[212:213] op_sel_hi:[0,1]
	v_pk_mul_f32 v[142:143], v[190:191], v[224:225] op_sel_hi:[0,1]
	v_pk_mul_f32 v[144:145], v[190:191], v[226:227] op_sel_hi:[0,1]
	v_pk_mul_f32 v[210:211], v[190:191], v[132:133] op_sel_hi:[0,1]
	v_pk_mul_f32 v[212:213], v[190:191], v[130:131] op_sel_hi:[0,1]
	v_pk_mul_f32 v[224:225], v[190:191], v[136:137] op_sel_hi:[0,1]
	v_pk_mul_f32 v[136:137], v[190:191], v[134:135] op_sel_hi:[0,1]
	v_cvt_pk_bf16_f32 v130, v140, v141
	v_cvt_pk_bf16_f32 v131, v138, v139
	v_cvt_pk_bf16_f32 v132, v144, v145
	v_cvt_pk_bf16_f32 v133, v142, v143
	v_cvt_pk_bf16_f32 v134, v212, v213
	v_cvt_pk_bf16_f32 v135, v210, v211
	v_cvt_pk_bf16_f32 v136, v136, v137
	v_cvt_pk_bf16_f32 v137, v224, v225
	global_store_dwordx4 v[194:195], v[130:133], off
	global_store_dwordx4 v[206:207], v[134:137], off
	global_load_dwordx4 v[130:133], v[208:209], off
	s_nop 0
	global_load_dwordx4 v[134:137], v[208:209], off offset:16
	v_lshl_add_u64 v[142:143], v[172:173], 0, v[178:179]
	global_load_dwordx4 v[138:141], v[142:143], off
	s_nop 0
	global_load_dwordx4 v[142:145], v[142:143], off offset:16
	global_load_dword v223, v[188:189], off
	global_load_dword v223, v[188:189], off
	v_mul_f32_e32 v190, v166, v222
	v_and_b32_e32 v178, 0xfef, v220
	v_mad_i64_i32 v[194:195], s[6:7], v219, s33, v[174:175]
	v_mul_u32_u24_e32 v178, s0, v178
	v_lshl_add_u64 v[194:195], v[194:195], 0, v[176:177]
	v_lshlrev_b32_e32 v178, 2, v178
	v_lshl_add_u64 v[206:207], v[194:195], 0, s[58:59]
	v_lshl_add_u64 v[208:209], v[188:189], 0, v[178:179]
	s_waitcnt vmcnt(5)
	v_pk_mul_f32 v[210:211], v[36:37], v[132:133]
	v_pk_mul_f32 v[212:213], v[34:35], v[130:131]
	s_waitcnt vmcnt(4)
	v_pk_mul_f32 v[224:225], v[28:29], v[136:137]
	v_pk_mul_f32 v[226:227], v[26:27], v[134:135]
	v_pk_mul_f32 v[132:133], v[56:57], v[132:133]
	v_pk_mul_f32 v[130:131], v[54:55], v[130:131]
	v_pk_mul_f32 v[136:137], v[48:49], v[136:137]
	v_pk_mul_f32 v[134:135], v[46:47], v[134:135]
	s_waitcnt vmcnt(3)
	v_pk_fma_f32 v[210:211], v[56:57], v[140:141], v[210:211] neg_lo:[0,0,1] neg_hi:[0,0,1]
	v_pk_fma_f32 v[212:213], v[54:55], v[138:139], v[212:213] neg_lo:[0,0,1] neg_hi:[0,0,1]
	s_waitcnt vmcnt(2)
; __device__ __forceinline__ u32x4 pack8(const f32x4& a, const f32x4& b) { u32x4 w; w.x = cvt_pk_bf16(a[0], a[1]); w.y = cvt_pk_bf16(a[2], a[3]); w.z = cvt_pk_bf16(b[0], b[1]); w.w = cvt_pk_bf16(b[2], b[3]); return w; }
;     __device__ __forceinline__ void operator()(const f32x4 (&acc)[2][2][4][2], const Unit& u, int wr, int wc, int fr, int fq) const {
;     ...
;                 for (int m = 0; m < 4; ++m) { const int row = row0 + ai * HALF + m * 16, pos = row & (SEQ - 1); const float scr = sc * rs[ai][m];
;                     const f32x4 c0 = *(const f32x4*)(ct + pos * tp + i0), c1 = *(const f32x4*)(ct + pos * tp + i0 + 4), s0 = *(const f32x4*)(st + pos * tp + i0), s1 = *(const f32x4*)(st + pos * tp + i0 + 4);
;                     const f32x4 x10 = acc[ai][0][m][0], x11 = acc[ai][0][m][1], x20 = acc[ai][1][m][0], x21 = acc[ai][1][m][1];
;                     const f32x4 a0 = (x10 * c0 - x20 * s0) * scr, a1 = (x11 * c1 - x21 * s1) * scr, b0 = (x10 * s0 + x20 * c0) * scr, b1 = (x11 * s1 + x21 * c1) * scr;
;                     bf16_t* rowp = O + (size_t)row * LDP + d1;
;                     *(u32x4*)(rowp) = pack8(a0, a1); *(u32x4*)(rowp + dd) = pack8(b0, b1); }
	v_pk_fma_f32 v[224:225], v[48:49], v[144:145], v[224:225] neg_lo:[0,0,1] neg_hi:[0,0,1]
	v_pk_fma_f32 v[226:227], v[46:47], v[142:143], v[226:227] neg_lo:[0,0,1] neg_hi:[0,0,1]
	v_pk_fma_f32 v[132:133], v[36:37], v[140:141], v[132:133]
	v_pk_fma_f32 v[130:131], v[34:35], v[138:139], v[130:131]
	v_pk_fma_f32 v[136:137], v[28:29], v[144:145], v[136:137]
	v_pk_fma_f32 v[134:135], v[26:27], v[142:143], v[134:135]
	v_pk_mul_f32 v[138:139], v[190:191], v[210:211] op_sel_hi:[0,1]
	v_pk_mul_f32 v[140:141], v[190:191], v[212:213] op_sel_hi:[0,1]
	v_pk_mul_f32 v[142:143], v[190:191], v[224:225] op_sel_hi:[0,1]
	v_pk_mul_f32 v[144:145], v[190:191], v[226:227] op_sel_hi:[0,1]
	v_pk_mul_f32 v[210:211], v[190:191], v[132:133] op_sel_hi:[0,1]
	v_pk_mul_f32 v[212:213], v[190:191], v[130:131] op_sel_hi:[0,1]
	v_pk_mul_f32 v[224:225], v[190:191], v[136:137] op_sel_hi:[0,1]
	v_pk_mul_f32 v[136:137], v[190:191], v[134:135] op_sel_hi:[0,1]
	v_cvt_pk_bf16_f32 v130, v140, v141
	v_cvt_pk_bf16_f32 v131, v138, v139
	v_cvt_pk_bf16_f32 v132, v144, v145
	v_cvt_pk_bf16_f32 v133, v142, v143
	v_cvt_pk_bf16_f32 v134, v212, v213
	v_cvt_pk_bf16_f32 v135, v210, v211
	v_cvt_pk_bf16_f32 v136, v136, v137
	v_cvt_pk_bf16_f32 v137, v224, v225
	global_store_dwordx4 v[194:195], v[130:133], off
	global_store_dwordx4 v[206:207], v[134:137], off
	global_load_dwordx4 v[130:133], v[208:209], off
	s_nop 0
	global_load_dwordx4 v[134:137], v[208:209], off offset:16
	v_lshl_add_u64 v[142:143], v[172:173], 0, v[178:179]
	global_load_dwordx4 v[138:141], v[142:143], off
	s_nop 0
	global_load_dwordx4 v[142:145], v[142:143], off offset:16
	global_load_dword v223, v[188:189], off
	global_load_dword v223, v[188:189], off
	v_mul_f32_e32 v190, v170, v222
	v_and_b32_e32 v178, 0xfff, v221
	v_mad_i64_i32 v[194:195], s[6:7], v220, s33, v[174:175]
	v_mul_u32_u24_e32 v178, s0, v178
	v_lshl_add_u64 v[194:195], v[194:195], 0, v[176:177]
	v_lshlrev_b32_e32 v178, 2, v178
	v_lshl_add_u64 v[206:207], v[194:195], 0, s[58:59]
	v_lshl_add_u64 v[188:189], v[188:189], 0, v[178:179]
	v_mad_i64_i32 v[174:175], s[0:1], v221, s33, v[174:175]
	v_lshl_add_u64 v[174:175], v[174:175], 0, v[176:177]
	v_lshl_add_u64 v[176:177], v[174:175], 0, s[58:59]
	s_waitcnt vmcnt(5)
	v_pk_mul_f32 v[208:209], v[20:21], v[132:133]
	v_pk_mul_f32 v[210:211], v[18:19], v[130:131]
	s_waitcnt vmcnt(4)
	v_pk_mul_f32 v[212:213], v[12:13], v[136:137]
	v_pk_mul_f32 v[224:225], v[10:11], v[134:135]
	v_pk_mul_f32 v[132:133], v[40:41], v[132:133]
	v_pk_mul_f32 v[130:131], v[38:39], v[130:131]
	v_pk_mul_f32 v[136:137], v[32:33], v[136:137]
	v_pk_mul_f32 v[134:135], v[30:31], v[134:135]
	s_waitcnt vmcnt(3)
	v_pk_fma_f32 v[208:209], v[40:41], v[140:141], v[208:209] neg_lo:[0,0,1] neg_hi:[0,0,1]
	v_pk_fma_f32 v[210:211], v[38:39], v[138:139], v[210:211] neg_lo:[0,0,1] neg_hi:[0,0,1]
	s_waitcnt vmcnt(2)
	v_pk_fma_f32 v[212:213], v[32:33], v[144:145], v[212:213] neg_lo:[0,0,1] neg_hi:[0,0,1]
	v_pk_fma_f32 v[224:225], v[30:31], v[142:143], v[224:225] neg_lo:[0,0,1] neg_hi:[0,0,1]
	v_pk_fma_f32 v[132:133], v[20:21], v[140:141], v[132:133]
	v_pk_fma_f32 v[130:131], v[18:19], v[138:139], v[130:131]
	v_pk_fma_f32 v[136:137], v[12:13], v[144:145], v[136:137]
	v_pk_fma_f32 v[134:135], v[10:11], v[142:143], v[134:135]
	v_pk_mul_f32 v[138:139], v[190:191], v[208:209] op_sel_hi:[0,1]
	v_pk_mul_f32 v[140:141], v[190:191], v[210:211] op_sel_hi:[0,1]
	v_pk_mul_f32 v[142:143], v[190:191], v[212:213] op_sel_hi:[0,1]
	v_pk_mul_f32 v[144:145], v[190:191], v[224:225] op_sel_hi:[0,1]
	v_pk_mul_f32 v[208:209], v[190:191], v[132:133] op_sel_hi:[0,1]
	v_pk_mul_f32 v[210:211], v[190:191], v[130:131] op_sel_hi:[0,1]
	v_pk_mul_f32 v[212:213], v[190:191], v[136:137] op_sel_hi:[0,1]
	v_pk_mul_f32 v[136:137], v[190:191], v[134:135] op_sel_hi:[0,1]
	v_cvt_pk_bf16_f32 v130, v140, v141
	v_cvt_pk_bf16_f32 v131, v138, v139
	v_cvt_pk_bf16_f32 v132, v144, v145
	v_cvt_pk_bf16_f32 v133, v142, v143
	v_cvt_pk_bf16_f32 v134, v210, v211
	v_cvt_pk_bf16_f32 v135, v208, v209
	v_cvt_pk_bf16_f32 v136, v136, v137
	v_cvt_pk_bf16_f32 v137, v212, v213
	global_store_dwordx4 v[194:195], v[130:133], off
	global_store_dwordx4 v[206:207], v[134:137], off
	global_load_dwordx4 v[130:133], v[188:189], off
	s_nop 0
	global_load_dwordx4 v[134:137], v[188:189], off offset:16
	v_lshl_add_u64 v[142:143], v[172:173], 0, v[178:179]
	global_load_dwordx4 v[138:141], v[142:143], off
	s_nop 0
	global_load_dwordx4 v[142:145], v[142:143], off offset:16
	v_mul_f32_e32 v172, v168, v222
	s_waitcnt vmcnt(3)
	v_pk_mul_f32 v[188:189], v[8:9], v[132:133]
	v_pk_mul_f32 v[194:195], v[6:7], v[130:131]
	s_waitcnt vmcnt(2)
	v_pk_mul_f32 v[206:207], v[4:5], v[136:137]
	v_pk_mul_f32 v[208:209], v[2:3], v[134:135]
	v_pk_mul_f32 v[132:133], v[24:25], v[132:133]
	v_pk_mul_f32 v[130:131], v[22:23], v[130:131]
	v_pk_mul_f32 v[136:137], v[16:17], v[136:137]
	v_pk_mul_f32 v[134:135], v[14:15], v[134:135]
	s_waitcnt vmcnt(1)
	v_pk_fma_f32 v[188:189], v[24:25], v[140:141], v[188:189] neg_lo:[0,0,1] neg_hi:[0,0,1]
	v_pk_fma_f32 v[194:195], v[22:23], v[138:139], v[194:195] neg_lo:[0,0,1] neg_hi:[0,0,1]
	s_waitcnt vmcnt(0)
	v_pk_fma_f32 v[206:207], v[16:17], v[144:145], v[206:207] neg_lo:[0,0,1] neg_hi:[0,0,1]
	v_pk_fma_f32 v[208:209], v[14:15], v[142:143], v[208:209] neg_lo:[0,0,1] neg_hi:[0,0,1]
	v_pk_fma_f32 v[132:133], v[8:9], v[140:141], v[132:133]
	v_pk_fma_f32 v[130:131], v[6:7], v[138:139], v[130:131]
	v_pk_fma_f32 v[136:137], v[4:5], v[144:145], v[136:137]
	v_pk_fma_f32 v[134:135], v[2:3], v[142:143], v[134:135]
	v_pk_mul_f32 v[138:139], v[172:173], v[188:189] op_sel_hi:[0,1]
	v_pk_mul_f32 v[140:141], v[172:173], v[194:195] op_sel_hi:[0,1]
	v_pk_mul_f32 v[142:143], v[172:173], v[206:207] op_sel_hi:[0,1]
	v_pk_mul_f32 v[144:145], v[172:173], v[208:209] op_sel_hi:[0,1]
	v_pk_mul_f32 v[188:189], v[172:173], v[132:133] op_sel_hi:[0,1]
	v_pk_mul_f32 v[194:195], v[172:173], v[130:131] op_sel_hi:[0,1]
	v_pk_mul_f32 v[206:207], v[172:173], v[136:137] op_sel_hi:[0,1]
	v_pk_mul_f32 v[136:137], v[172:173], v[134:135] op_sel_hi:[0,1]
	v_cvt_pk_bf16_f32 v130, v140, v141
	v_cvt_pk_bf16_f32 v131, v138, v139
	v_cvt_pk_bf16_f32 v132, v144, v145
	v_cvt_pk_bf16_f32 v133, v142, v143
	v_cvt_pk_bf16_f32 v134, v194, v195
	v_cvt_pk_bf16_f32 v135, v188, v189
	v_cvt_pk_bf16_f32 v136, v136, v137
	v_cvt_pk_bf16_f32 v137, v206, v207
	global_store_dwordx4 v[174:175], v[130:133], off
	global_store_dwordx4 v[176:177], v[134:137], off
	s_branch .LBB0_289
